# last unit of 8 GEMM phases (16-byte epilogue stores) publishes with write-through sc1 stores; on top of barrier edits
# baseline (speedup 1.0000x reference)
.LBB0_267:
	s_and_b64 vcc, exec, s[4:5]
	s_cbranch_vccnz .Lepi_wt_0
	v_lshl_add_u32 v152, s82, 8, v146
	v_lshl_or_b32 v144, s83, 8, v148
	v_ashrrev_i32_e32 v145, 31, v144
	v_ashrrev_i32_e32 v153, 31, v152
	v_lshl_add_u64 v[154:155], v[144:145], 1, s[24:25]
	v_lshlrev_b64 v[144:145], 11, v[152:153]
	v_lshl_add_u64 v[144:145], v[154:155], 0, v[144:145]
	s_nop 15
	s_nop 7
	v_cvt_pk_bf16_f32 v124, v124, v125
	v_cvt_pk_bf16_f32 v125, v126, v127
	v_cvt_pk_bf16_f32 v126, v120, v121
	v_cvt_pk_bf16_f32 v127, v122, v123
	global_store_dwordx4 v[144:145], v[124:127], off
	v_cvt_pk_bf16_f32 v112, v112, v113
	v_cvt_pk_bf16_f32 v113, v114, v115
	v_cvt_pk_bf16_f32 v114, v104, v105
	v_or_b32_e32 v104, 16, v152
	v_ashrrev_i32_e32 v105, 31, v104
	v_lshlrev_b64 v[104:105], 11, v[104:105]
	v_cvt_pk_bf16_f32 v115, v106, v107
	global_store_dwordx4 v[144:145], v[112:115], off offset:256
	s_nop 1
	v_lshl_add_u64 v[112:113], v[154:155], 0, v[104:105]
	v_cvt_pk_bf16_f32 v104, v116, v117
	v_cvt_pk_bf16_f32 v105, v118, v119
	v_cvt_pk_bf16_f32 v106, v108, v109
	v_cvt_pk_bf16_f32 v107, v110, v111
	global_store_dwordx4 v[112:113], v[104:107], off
	v_cvt_pk_bf16_f32 v96, v96, v97
	v_cvt_pk_bf16_f32 v97, v98, v99
	v_cvt_pk_bf16_f32 v98, v88, v89
	v_or_b32_e32 v88, 32, v152
	v_ashrrev_i32_e32 v89, 31, v88
	v_lshlrev_b64 v[88:89], 11, v[88:89]
	v_cvt_pk_bf16_f32 v99, v90, v91
	global_store_dwordx4 v[112:113], v[96:99], off offset:256
	s_nop 1
	v_lshl_add_u64 v[96:97], v[154:155], 0, v[88:89]
	v_cvt_pk_bf16_f32 v88, v100, v101
	v_cvt_pk_bf16_f32 v89, v102, v103
	v_cvt_pk_bf16_f32 v90, v92, v93
	v_cvt_pk_bf16_f32 v91, v94, v95
	global_store_dwordx4 v[96:97], v[88:91], off
	v_cvt_pk_bf16_f32 v80, v80, v81
	v_cvt_pk_bf16_f32 v81, v82, v83
	v_cvt_pk_bf16_f32 v82, v72, v73
	v_or_b32_e32 v72, 48, v152
	v_ashrrev_i32_e32 v73, 31, v72
	v_lshlrev_b64 v[72:73], 11, v[72:73]
	v_cvt_pk_bf16_f32 v83, v74, v75
	global_store_dwordx4 v[96:97], v[80:83], off offset:256
	s_nop 1
	v_lshl_add_u64 v[80:81], v[154:155], 0, v[72:73]
	v_cvt_pk_bf16_f32 v72, v84, v85
	v_cvt_pk_bf16_f32 v73, v86, v87
	v_cvt_pk_bf16_f32 v74, v76, v77
	v_cvt_pk_bf16_f32 v75, v78, v79
	global_store_dwordx4 v[80:81], v[72:75], off
	v_cvt_pk_bf16_f32 v68, v68, v69
	v_cvt_pk_bf16_f32 v69, v70, v71
	v_cvt_pk_bf16_f32 v70, v64, v65
	v_cvt_pk_bf16_f32 v71, v66, v67
	global_store_dwordx4 v[80:81], v[68:71], off offset:256
	v_cvt_pk_bf16_f32 v60, v60, v61
	v_cvt_pk_bf16_f32 v61, v62, v63
	v_cvt_pk_bf16_f32 v62, v56, v57
	v_add_co_u32_e32 v56, vcc, s72, v144
	v_lshl_add_u64 v[64:65], v[144:145], 0, s[30:31]
	s_nop 0
	v_addc_co_u32_e32 v57, vcc, 0, v145, vcc
	v_cvt_pk_bf16_f32 v63, v58, v59
	global_store_dwordx4 v[56:57], v[60:63], off
	v_cvt_pk_bf16_f32 v48, v48, v49
	v_cvt_pk_bf16_f32 v49, v50, v51
	v_cvt_pk_bf16_f32 v50, v40, v41
	v_cvt_pk_bf16_f32 v51, v42, v43
	global_store_dwordx4 v[64:65], v[48:51], off offset:256
	v_cvt_pk_bf16_f32 v40, v52, v53
	v_cvt_pk_bf16_f32 v41, v54, v55
	v_cvt_pk_bf16_f32 v42, v44, v45
	v_add_co_u32_e32 v44, vcc, s73, v144
	s_nop 0
	v_lshl_add_u64 v[48:49], v[144:145], 0, s[36:37]
	v_addc_co_u32_e32 v45, vcc, 0, v145, vcc
	v_cvt_pk_bf16_f32 v43, v46, v47
	global_store_dwordx4 v[44:45], v[40:43], off
	v_cvt_pk_bf16_f32 v32, v32, v33
	v_cvt_pk_bf16_f32 v33, v34, v35
	v_cvt_pk_bf16_f32 v34, v24, v25
	v_cvt_pk_bf16_f32 v35, v26, v27
	global_store_dwordx4 v[48:49], v[32:35], off offset:256
	v_cvt_pk_bf16_f32 v24, v36, v37
	v_cvt_pk_bf16_f32 v25, v38, v39
	v_cvt_pk_bf16_f32 v26, v28, v29
	v_add_co_u32_e32 v28, vcc, s74, v144
	s_nop 0
	v_lshl_add_u64 v[32:33], v[144:145], 0, s[44:45]
	v_addc_co_u32_e32 v29, vcc, 0, v145, vcc
	v_cvt_pk_bf16_f32 v27, v30, v31
	global_store_dwordx4 v[28:29], v[24:27], off
	v_cvt_pk_bf16_f32 v16, v16, v17
	v_cvt_pk_bf16_f32 v17, v18, v19
	v_cvt_pk_bf16_f32 v18, v8, v9
	v_cvt_pk_bf16_f32 v19, v10, v11
	global_store_dwordx4 v[32:33], v[16:19], off offset:256
	v_cvt_pk_bf16_f32 v8, v20, v21
	v_cvt_pk_bf16_f32 v9, v22, v23
	v_cvt_pk_bf16_f32 v10, v12, v13
	v_add_co_u32_e32 v12, vcc, s75, v144
	s_nop 0
	v_lshl_add_u64 v[16:17], v[144:145], 0, s[46:47]
	v_addc_co_u32_e32 v13, vcc, 0, v145, vcc
	s_and_b64 vcc, exec, s[4:5]
	s_mov_b64 s[4:5], -1
	v_cvt_pk_bf16_f32 v11, v14, v15
	global_store_dwordx4 v[12:13], v[8:11], off
	v_cvt_pk_bf16_f32 v4, v4, v5
	v_cvt_pk_bf16_f32 v5, v6, v7
	v_cvt_pk_bf16_f32 v6, v0, v1
	v_cvt_pk_bf16_f32 v7, v2, v3
	global_store_dwordx4 v[16:17], v[4:7], off offset:256
	s_cbranch_vccnz .LBB0_252
	s_andn2_b64 vcc, exec, s[0:1]
	s_cbranch_vccnz .LBB0_251
	s_barrier
	s_branch .LBB0_251

.LBB0_390:
	s_andn2_b64 vcc, exec, s[4:5]
	s_cbranch_vccnz .Lepi_wt_1
	s_lshl_b32 s18, s57, 8
	s_or_b32 s18, s18, s73
	v_lshl_add_u32 v152, s56, 8, v146
	s_ashr_i32 s56, s18, 6
	s_ashr_i32 s57, s56, 31
	s_lshl_b64 s[58:59], s[56:57], 22
	s_cmp_lt_i32 s56, 16
	s_cselect_b64 vcc, -1, 0
	v_cndmask_b32_e32 v156, 1.0, v151, vcc
	v_pk_mul_f32 v[124:125], v[156:157], v[124:125] op_sel_hi:[0,1]
	v_ashrrev_i32_e32 v153, 31, v152
	v_lshl_add_u64 v[154:155], v[136:137], 0, s[58:59]
	v_pk_mul_f32 v[126:127], v[156:157], v[126:127] op_sel_hi:[0,1]
	v_pk_mul_f32 v[158:159], v[156:157], v[122:123] op_sel_hi:[0,1]
	v_pk_mul_f32 v[122:123], v[156:157], v[120:121] op_sel_hi:[0,1]
	v_cvt_pk_bf16_f32 v120, v124, v125
	v_lshlrev_b64 v[124:125], 7, v[152:153]
	v_cvt_pk_bf16_f32 v121, v126, v127
	v_lshl_add_u64 v[126:127], v[154:155], 0, v[124:125]
	v_pk_mul_f32 v[116:117], v[156:157], v[116:117] op_sel_hi:[0,1]
	v_cvt_pk_bf16_f32 v122, v122, v123
	v_cvt_pk_bf16_f32 v123, v158, v159
	global_store_dwordx4 v[126:127], v[120:123], off
	v_pk_mul_f32 v[118:119], v[156:157], v[118:119] op_sel_hi:[0,1]
	v_pk_mul_f32 v[108:109], v[156:157], v[108:109] op_sel_hi:[0,1]
	v_pk_mul_f32 v[120:121], v[156:157], v[114:115] op_sel_hi:[0,1]
	v_pk_mul_f32 v[114:115], v[156:157], v[112:113] op_sel_hi:[0,1]
	v_cvt_pk_bf16_f32 v112, v116, v117
	v_or_b32_e32 v116, 16, v152
	v_ashrrev_i32_e32 v117, 31, v116
	v_lshlrev_b64 v[116:117], 7, v[116:117]
	v_cvt_pk_bf16_f32 v113, v118, v119
	v_lshl_add_u64 v[118:119], v[154:155], 0, v[116:117]
	v_cvt_pk_bf16_f32 v114, v114, v115
	v_cvt_pk_bf16_f32 v115, v120, v121
	global_store_dwordx4 v[118:119], v[112:115], off
	v_pk_mul_f32 v[110:111], v[156:157], v[110:111] op_sel_hi:[0,1]
	v_pk_mul_f32 v[100:101], v[156:157], v[100:101] op_sel_hi:[0,1]
	v_pk_mul_f32 v[112:113], v[156:157], v[106:107] op_sel_hi:[0,1]
	v_pk_mul_f32 v[106:107], v[156:157], v[104:105] op_sel_hi:[0,1]
	v_cvt_pk_bf16_f32 v104, v108, v109
	v_or_b32_e32 v108, 32, v152
	v_ashrrev_i32_e32 v109, 31, v108
	v_lshlrev_b64 v[108:109], 7, v[108:109]
	v_cvt_pk_bf16_f32 v105, v110, v111
	v_lshl_add_u64 v[110:111], v[154:155], 0, v[108:109]
	v_cvt_pk_bf16_f32 v106, v106, v107
	v_cvt_pk_bf16_f32 v107, v112, v113
	global_store_dwordx4 v[110:111], v[104:107], off
	v_pk_mul_f32 v[102:103], v[156:157], v[102:103] op_sel_hi:[0,1]
	v_pk_mul_f32 v[92:93], v[156:157], v[92:93] op_sel_hi:[0,1]
	v_pk_mul_f32 v[104:105], v[156:157], v[98:99] op_sel_hi:[0,1]
	v_pk_mul_f32 v[98:99], v[156:157], v[96:97] op_sel_hi:[0,1]
	v_cvt_pk_bf16_f32 v96, v100, v101
	v_or_b32_e32 v100, 48, v152
	v_ashrrev_i32_e32 v101, 31, v100
	v_lshlrev_b64 v[100:101], 7, v[100:101]
	v_cvt_pk_bf16_f32 v97, v102, v103
	v_lshl_add_u64 v[102:103], v[154:155], 0, v[100:101]
	v_cvt_pk_bf16_f32 v98, v98, v99
	v_cvt_pk_bf16_f32 v99, v104, v105
	global_store_dwordx4 v[102:103], v[96:99], off
	v_pk_mul_f32 v[94:95], v[156:157], v[94:95] op_sel_hi:[0,1]
	v_pk_mul_f32 v[84:85], v[156:157], v[84:85] op_sel_hi:[0,1]
	v_pk_mul_f32 v[96:97], v[156:157], v[90:91] op_sel_hi:[0,1]
	v_pk_mul_f32 v[90:91], v[156:157], v[88:89] op_sel_hi:[0,1]
	v_cvt_pk_bf16_f32 v88, v92, v93
	v_lshl_add_u64 v[92:93], v[124:125], 0, s[10:11]
	v_cvt_pk_bf16_f32 v89, v94, v95
	v_lshl_add_u64 v[94:95], v[154:155], 0, v[92:93]
	v_cvt_pk_bf16_f32 v90, v90, v91
	v_cvt_pk_bf16_f32 v91, v96, v97
	global_store_dwordx4 v[94:95], v[88:91], off
	v_pk_mul_f32 v[86:87], v[156:157], v[86:87] op_sel_hi:[0,1]
	s_or_b32 s56, s56, 2
	v_pk_mul_f32 v[88:89], v[156:157], v[82:83] op_sel_hi:[0,1]
	v_pk_mul_f32 v[82:83], v[156:157], v[80:81] op_sel_hi:[0,1]
	v_cvt_pk_bf16_f32 v80, v84, v85
	v_lshl_add_u64 v[84:85], v[124:125], 0, s[16:17]
	v_cvt_pk_bf16_f32 v81, v86, v87
	v_lshl_add_u64 v[86:87], v[154:155], 0, v[84:85]
	v_pk_mul_f32 v[76:77], v[156:157], v[76:77] op_sel_hi:[0,1]
	s_ashr_i32 s57, s56, 31
	v_cvt_pk_bf16_f32 v82, v82, v83
	v_cvt_pk_bf16_f32 v83, v88, v89
	global_store_dwordx4 v[86:87], v[80:83], off
	v_pk_mul_f32 v[78:79], v[156:157], v[78:79] op_sel_hi:[0,1]
	s_lshl_b64 s[58:59], s[56:57], 22
	v_pk_mul_f32 v[80:81], v[156:157], v[74:75] op_sel_hi:[0,1]
	v_pk_mul_f32 v[74:75], v[156:157], v[72:73] op_sel_hi:[0,1]
	v_cvt_pk_bf16_f32 v72, v76, v77
	v_lshl_add_u64 v[76:77], v[124:125], 0, s[36:37]
	v_cvt_pk_bf16_f32 v73, v78, v79
	v_lshl_add_u64 v[78:79], v[154:155], 0, v[76:77]
	v_pk_mul_f32 v[60:61], v[156:157], v[60:61] op_sel_hi:[0,1]
	s_cmp_lt_i32 s56, 16
	v_cvt_pk_bf16_f32 v74, v74, v75
	v_cvt_pk_bf16_f32 v75, v80, v81
	global_store_dwordx4 v[78:79], v[72:75], off
	v_pk_mul_f32 v[62:63], v[156:157], v[62:63] op_sel_hi:[0,1]
	s_cselect_b64 vcc, -1, 0
	v_pk_mul_f32 v[72:73], v[156:157], v[58:59] op_sel_hi:[0,1]
	v_pk_mul_f32 v[58:59], v[156:157], v[56:57] op_sel_hi:[0,1]
	v_cvt_pk_bf16_f32 v56, v60, v61
	v_lshl_add_u64 v[60:61], v[124:125], 0, s[44:45]
	v_cvt_pk_bf16_f32 v57, v62, v63
	v_cvt_pk_bf16_f32 v58, v58, v59
	v_cvt_pk_bf16_f32 v59, v72, v73
	v_lshl_add_u64 v[62:63], v[154:155], 0, v[60:61]
	v_cndmask_b32_e32 v72, 1.0, v151, vcc
	global_store_dwordx4 v[62:63], v[56:59], off
	v_lshl_add_u64 v[62:63], v[136:137], 0, s[58:59]
	v_pk_mul_f32 v[64:65], v[72:73], v[64:65] op_sel_hi:[0,1]
	v_pk_mul_f32 v[58:59], v[72:73], v[70:71] op_sel_hi:[0,1]
	v_pk_mul_f32 v[56:57], v[72:73], v[68:69] op_sel_hi:[0,1]
	v_cvt_pk_bf16_f32 v56, v56, v57
	v_cvt_pk_bf16_f32 v57, v58, v59
	v_cvt_pk_bf16_f32 v58, v64, v65
	v_lshl_add_u64 v[64:65], v[62:63], 0, v[124:125]
	v_pk_mul_f32 v[52:53], v[72:73], v[52:53] op_sel_hi:[0,1]
	v_pk_mul_f32 v[66:67], v[72:73], v[66:67] op_sel_hi:[0,1]
	v_cvt_pk_bf16_f32 v59, v66, v67
	global_store_dwordx4 v[64:65], v[56:59], off
	v_pk_mul_f32 v[54:55], v[72:73], v[54:55] op_sel_hi:[0,1]
	v_pk_mul_f32 v[44:45], v[72:73], v[44:45] op_sel_hi:[0,1]
	v_pk_mul_f32 v[56:57], v[72:73], v[50:51] op_sel_hi:[0,1]
	v_pk_mul_f32 v[50:51], v[72:73], v[48:49] op_sel_hi:[0,1]
	v_cvt_pk_bf16_f32 v48, v52, v53
	v_cvt_pk_bf16_f32 v49, v54, v55
	v_lshl_add_u64 v[52:53], v[62:63], 0, v[116:117]
	v_cvt_pk_bf16_f32 v50, v50, v51
	v_cvt_pk_bf16_f32 v51, v56, v57
	global_store_dwordx4 v[52:53], v[48:51], off
	v_pk_mul_f32 v[46:47], v[72:73], v[46:47] op_sel_hi:[0,1]
	v_pk_mul_f32 v[36:37], v[72:73], v[36:37] op_sel_hi:[0,1]
	v_pk_mul_f32 v[48:49], v[72:73], v[42:43] op_sel_hi:[0,1]
	v_pk_mul_f32 v[42:43], v[72:73], v[40:41] op_sel_hi:[0,1]
	v_cvt_pk_bf16_f32 v40, v44, v45
	v_cvt_pk_bf16_f32 v41, v46, v47
	v_lshl_add_u64 v[44:45], v[62:63], 0, v[108:109]
	v_cvt_pk_bf16_f32 v42, v42, v43
	v_cvt_pk_bf16_f32 v43, v48, v49
	global_store_dwordx4 v[44:45], v[40:43], off
	v_pk_mul_f32 v[38:39], v[72:73], v[38:39] op_sel_hi:[0,1]
	v_pk_mul_f32 v[28:29], v[72:73], v[28:29] op_sel_hi:[0,1]
	v_pk_mul_f32 v[40:41], v[72:73], v[34:35] op_sel_hi:[0,1]
	v_pk_mul_f32 v[34:35], v[72:73], v[32:33] op_sel_hi:[0,1]
	v_cvt_pk_bf16_f32 v32, v36, v37
	v_cvt_pk_bf16_f32 v33, v38, v39
	v_lshl_add_u64 v[36:37], v[62:63], 0, v[100:101]
	v_cvt_pk_bf16_f32 v34, v34, v35
	v_cvt_pk_bf16_f32 v35, v40, v41
	global_store_dwordx4 v[36:37], v[32:35], off
	v_pk_mul_f32 v[30:31], v[72:73], v[30:31] op_sel_hi:[0,1]
	v_pk_mul_f32 v[20:21], v[72:73], v[20:21] op_sel_hi:[0,1]
	v_pk_mul_f32 v[32:33], v[72:73], v[26:27] op_sel_hi:[0,1]
	v_pk_mul_f32 v[26:27], v[72:73], v[24:25] op_sel_hi:[0,1]
	v_cvt_pk_bf16_f32 v24, v28, v29
	v_cvt_pk_bf16_f32 v25, v30, v31
	v_lshl_add_u64 v[28:29], v[62:63], 0, v[92:93]
	v_cvt_pk_bf16_f32 v26, v26, v27
	v_cvt_pk_bf16_f32 v27, v32, v33
	global_store_dwordx4 v[28:29], v[24:27], off
	v_pk_mul_f32 v[22:23], v[72:73], v[22:23] op_sel_hi:[0,1]
	v_pk_mul_f32 v[12:13], v[72:73], v[12:13] op_sel_hi:[0,1]
	v_pk_mul_f32 v[24:25], v[72:73], v[18:19] op_sel_hi:[0,1]
	v_pk_mul_f32 v[18:19], v[72:73], v[16:17] op_sel_hi:[0,1]
	v_cvt_pk_bf16_f32 v16, v20, v21
	v_cvt_pk_bf16_f32 v17, v22, v23
	v_lshl_add_u64 v[20:21], v[62:63], 0, v[84:85]
	v_cvt_pk_bf16_f32 v18, v18, v19
	v_cvt_pk_bf16_f32 v19, v24, v25
	global_store_dwordx4 v[20:21], v[16:19], off
	v_pk_mul_f32 v[14:15], v[72:73], v[14:15] op_sel_hi:[0,1]
	v_pk_mul_f32 v[4:5], v[72:73], v[4:5] op_sel_hi:[0,1]
	v_pk_mul_f32 v[16:17], v[72:73], v[10:11] op_sel_hi:[0,1]
	v_pk_mul_f32 v[10:11], v[72:73], v[8:9] op_sel_hi:[0,1]
	v_cvt_pk_bf16_f32 v8, v12, v13
	v_cvt_pk_bf16_f32 v9, v14, v15
	v_lshl_add_u64 v[12:13], v[62:63], 0, v[76:77]
	v_cvt_pk_bf16_f32 v10, v10, v11
	v_cvt_pk_bf16_f32 v11, v16, v17
	global_store_dwordx4 v[12:13], v[8:11], off
	s_andn2_b64 vcc, exec, s[4:5]
	s_mov_b64 s[4:5], -1
	v_pk_mul_f32 v[8:9], v[72:73], v[2:3] op_sel_hi:[0,1]
	v_pk_mul_f32 v[2:3], v[72:73], v[0:1] op_sel_hi:[0,1]
	v_cvt_pk_bf16_f32 v0, v4, v5
	v_lshl_add_u64 v[4:5], v[62:63], 0, v[60:61]
	v_pk_mul_f32 v[6:7], v[72:73], v[6:7] op_sel_hi:[0,1]
	v_cvt_pk_bf16_f32 v1, v6, v7
	v_cvt_pk_bf16_f32 v2, v2, v3
	v_cvt_pk_bf16_f32 v3, v8, v9
	global_store_dwordx4 v[4:5], v[0:3], off
	s_cbranch_vccnz .LBB0_383
	s_andn2_b64 vcc, exec, s[0:1]
	s_cbranch_vccnz .LBB0_382
	s_barrier
	s_branch .LBB0_382

.LBB0_604:
	s_andn2_b64 vcc, exec, s[4:5]
	s_cbranch_vccnz .Lepi_wt_2
	v_lshl_add_u32 v152, s56, 8, v146
	v_lshl_or_b32 v144, s83, 8, v148
	v_ashrrev_i32_e32 v145, 31, v144
	v_ashrrev_i32_e32 v153, 31, v152
	v_lshl_add_u64 v[154:155], v[144:145], 1, s[24:25]
	v_lshlrev_b64 v[144:145], 11, v[152:153]
	v_lshl_add_u64 v[144:145], v[154:155], 0, v[144:145]
	s_nop 15
	s_nop 7
	v_cvt_pk_bf16_f32 v124, v124, v125
	v_cvt_pk_bf16_f32 v125, v126, v127
	v_cvt_pk_bf16_f32 v126, v120, v121
	v_cvt_pk_bf16_f32 v127, v122, v123
	global_store_dwordx4 v[144:145], v[124:127], off
	v_cvt_pk_bf16_f32 v112, v112, v113
	v_cvt_pk_bf16_f32 v113, v114, v115
	v_cvt_pk_bf16_f32 v114, v104, v105
	v_or_b32_e32 v104, 16, v152
	v_ashrrev_i32_e32 v105, 31, v104
	v_lshlrev_b64 v[104:105], 11, v[104:105]
	v_cvt_pk_bf16_f32 v115, v106, v107
	global_store_dwordx4 v[144:145], v[112:115], off offset:256
	s_nop 1
	v_lshl_add_u64 v[112:113], v[154:155], 0, v[104:105]
	v_cvt_pk_bf16_f32 v104, v116, v117
	v_cvt_pk_bf16_f32 v105, v118, v119
	v_cvt_pk_bf16_f32 v106, v108, v109
	v_cvt_pk_bf16_f32 v107, v110, v111
	global_store_dwordx4 v[112:113], v[104:107], off
	v_cvt_pk_bf16_f32 v96, v96, v97
	v_cvt_pk_bf16_f32 v97, v98, v99
	v_cvt_pk_bf16_f32 v98, v88, v89
	v_or_b32_e32 v88, 32, v152
	v_ashrrev_i32_e32 v89, 31, v88
	v_lshlrev_b64 v[88:89], 11, v[88:89]
	v_cvt_pk_bf16_f32 v99, v90, v91
	global_store_dwordx4 v[112:113], v[96:99], off offset:256
	s_nop 1
	v_lshl_add_u64 v[96:97], v[154:155], 0, v[88:89]
	v_cvt_pk_bf16_f32 v88, v100, v101
	v_cvt_pk_bf16_f32 v89, v102, v103
	v_cvt_pk_bf16_f32 v90, v92, v93
	v_cvt_pk_bf16_f32 v91, v94, v95
	global_store_dwordx4 v[96:97], v[88:91], off
	v_cvt_pk_bf16_f32 v80, v80, v81
	v_cvt_pk_bf16_f32 v81, v82, v83
	v_cvt_pk_bf16_f32 v82, v72, v73
	v_or_b32_e32 v72, 48, v152
	v_ashrrev_i32_e32 v73, 31, v72
	v_lshlrev_b64 v[72:73], 11, v[72:73]
	v_cvt_pk_bf16_f32 v83, v74, v75
	global_store_dwordx4 v[96:97], v[80:83], off offset:256
	s_nop 1
	v_lshl_add_u64 v[80:81], v[154:155], 0, v[72:73]
	v_cvt_pk_bf16_f32 v72, v84, v85
	v_cvt_pk_bf16_f32 v73, v86, v87
	v_cvt_pk_bf16_f32 v74, v76, v77
	v_cvt_pk_bf16_f32 v75, v78, v79
	global_store_dwordx4 v[80:81], v[72:75], off
	v_cvt_pk_bf16_f32 v68, v68, v69
	v_cvt_pk_bf16_f32 v69, v70, v71
	v_cvt_pk_bf16_f32 v70, v64, v65
	v_cvt_pk_bf16_f32 v71, v66, v67
	global_store_dwordx4 v[80:81], v[68:71], off offset:256
	v_cvt_pk_bf16_f32 v60, v60, v61
	v_cvt_pk_bf16_f32 v61, v62, v63
	v_cvt_pk_bf16_f32 v62, v56, v57
	v_add_co_u32_e32 v56, vcc, s75, v144
	v_lshl_add_u64 v[64:65], v[144:145], 0, s[0:1]
	s_nop 0
	v_addc_co_u32_e32 v57, vcc, 0, v145, vcc
	v_cvt_pk_bf16_f32 v63, v58, v59
	global_store_dwordx4 v[56:57], v[60:63], off
	v_cvt_pk_bf16_f32 v48, v48, v49
	v_cvt_pk_bf16_f32 v49, v50, v51
	v_cvt_pk_bf16_f32 v50, v40, v41
	v_cvt_pk_bf16_f32 v51, v42, v43
	global_store_dwordx4 v[64:65], v[48:51], off offset:256
	v_cvt_pk_bf16_f32 v40, v52, v53
	v_cvt_pk_bf16_f32 v41, v54, v55
	v_cvt_pk_bf16_f32 v42, v44, v45
	v_add_co_u32_e32 v44, vcc, s76, v144
	s_nop 0
	v_lshl_add_u64 v[48:49], v[144:145], 0, s[16:17]
	v_addc_co_u32_e32 v45, vcc, 0, v145, vcc
	v_cvt_pk_bf16_f32 v43, v46, v47
	global_store_dwordx4 v[44:45], v[40:43], off
	v_cvt_pk_bf16_f32 v32, v32, v33
	v_cvt_pk_bf16_f32 v33, v34, v35
	v_cvt_pk_bf16_f32 v34, v24, v25
	v_cvt_pk_bf16_f32 v35, v26, v27
	global_store_dwordx4 v[48:49], v[32:35], off offset:256
	v_cvt_pk_bf16_f32 v24, v36, v37
	v_cvt_pk_bf16_f32 v25, v38, v39
	v_cvt_pk_bf16_f32 v26, v28, v29
	v_add_co_u32_e32 v28, vcc, s77, v144
	s_nop 0
	v_lshl_add_u64 v[32:33], v[144:145], 0, s[36:37]
	v_addc_co_u32_e32 v29, vcc, 0, v145, vcc
	v_cvt_pk_bf16_f32 v27, v30, v31
	global_store_dwordx4 v[28:29], v[24:27], off
	v_cvt_pk_bf16_f32 v16, v16, v17
	v_cvt_pk_bf16_f32 v17, v18, v19
	v_cvt_pk_bf16_f32 v18, v8, v9
	v_cvt_pk_bf16_f32 v19, v10, v11
	global_store_dwordx4 v[32:33], v[16:19], off offset:256
	v_cvt_pk_bf16_f32 v8, v20, v21
	v_cvt_pk_bf16_f32 v9, v22, v23
	v_cvt_pk_bf16_f32 v10, v12, v13
	v_add_co_u32_e32 v12, vcc, s82, v144
	s_nop 0
	v_lshl_add_u64 v[16:17], v[144:145], 0, s[44:45]
	v_addc_co_u32_e32 v13, vcc, 0, v145, vcc
	s_andn2_b64 vcc, exec, s[4:5]
	s_mov_b64 s[4:5], -1
	v_cvt_pk_bf16_f32 v11, v14, v15
	global_store_dwordx4 v[12:13], v[8:11], off
	v_cvt_pk_bf16_f32 v4, v4, v5
	v_cvt_pk_bf16_f32 v5, v6, v7
	v_cvt_pk_bf16_f32 v6, v0, v1
	v_cvt_pk_bf16_f32 v7, v2, v3
	global_store_dwordx4 v[16:17], v[4:7], off offset:256
	s_cbranch_vccnz .LBB0_593
	s_andn2_b64 vcc, exec, s[8:9]
	s_cbranch_vccnz .LBB0_592
	s_barrier
	s_branch .LBB0_592

.LBB0_807:
	s_and_b64 vcc, exec, s[10:11]
	s_cbranch_vccnz .Lepi_wt_3
	v_lshl_add_u32 v152, s82, 8, v146
	v_lshl_or_b32 v144, s83, 8, v148
	v_ashrrev_i32_e32 v145, 31, v144
	v_ashrrev_i32_e32 v153, 31, v152
	v_lshl_add_u64 v[154:155], v[144:145], 1, s[24:25]
	v_lshlrev_b64 v[144:145], 11, v[152:153]
	v_lshl_add_u64 v[144:145], v[154:155], 0, v[144:145]
	s_nop 15
	s_nop 7
	v_cvt_pk_bf16_f32 v124, v124, v125
	v_cvt_pk_bf16_f32 v125, v126, v127
	v_cvt_pk_bf16_f32 v126, v120, v121
	v_cvt_pk_bf16_f32 v127, v122, v123
	global_store_dwordx4 v[144:145], v[124:127], off
	v_cvt_pk_bf16_f32 v112, v112, v113
	v_cvt_pk_bf16_f32 v113, v114, v115
	v_cvt_pk_bf16_f32 v114, v104, v105
	v_or_b32_e32 v104, 16, v152
	v_ashrrev_i32_e32 v105, 31, v104
	v_lshlrev_b64 v[104:105], 11, v[104:105]
	v_cvt_pk_bf16_f32 v115, v106, v107
	global_store_dwordx4 v[144:145], v[112:115], off offset:256
	s_nop 1
	v_lshl_add_u64 v[112:113], v[154:155], 0, v[104:105]
	v_cvt_pk_bf16_f32 v104, v116, v117
	v_cvt_pk_bf16_f32 v105, v118, v119
	v_cvt_pk_bf16_f32 v106, v108, v109
	v_cvt_pk_bf16_f32 v107, v110, v111
	global_store_dwordx4 v[112:113], v[104:107], off
	v_cvt_pk_bf16_f32 v96, v96, v97
	v_cvt_pk_bf16_f32 v97, v98, v99
	v_cvt_pk_bf16_f32 v98, v88, v89
	v_or_b32_e32 v88, 32, v152
	v_ashrrev_i32_e32 v89, 31, v88
	v_lshlrev_b64 v[88:89], 11, v[88:89]
	v_cvt_pk_bf16_f32 v99, v90, v91
	global_store_dwordx4 v[112:113], v[96:99], off offset:256
	s_nop 1
	v_lshl_add_u64 v[96:97], v[154:155], 0, v[88:89]
	v_cvt_pk_bf16_f32 v88, v100, v101
	v_cvt_pk_bf16_f32 v89, v102, v103
	v_cvt_pk_bf16_f32 v90, v92, v93
	v_cvt_pk_bf16_f32 v91, v94, v95
	global_store_dwordx4 v[96:97], v[88:91], off
	v_cvt_pk_bf16_f32 v80, v80, v81
	v_cvt_pk_bf16_f32 v81, v82, v83
	v_cvt_pk_bf16_f32 v82, v72, v73
	v_or_b32_e32 v72, 48, v152
	v_ashrrev_i32_e32 v73, 31, v72
	v_lshlrev_b64 v[72:73], 11, v[72:73]
	v_cvt_pk_bf16_f32 v83, v74, v75
	global_store_dwordx4 v[96:97], v[80:83], off offset:256
	s_nop 1
	v_lshl_add_u64 v[80:81], v[154:155], 0, v[72:73]
	v_cvt_pk_bf16_f32 v72, v84, v85
	v_cvt_pk_bf16_f32 v73, v86, v87
	v_cvt_pk_bf16_f32 v74, v76, v77
	v_cvt_pk_bf16_f32 v75, v78, v79
	global_store_dwordx4 v[80:81], v[72:75], off
	v_cvt_pk_bf16_f32 v68, v68, v69
	v_cvt_pk_bf16_f32 v69, v70, v71
	v_cvt_pk_bf16_f32 v70, v64, v65
	v_cvt_pk_bf16_f32 v71, v66, v67
	global_store_dwordx4 v[80:81], v[68:71], off offset:256
	v_cvt_pk_bf16_f32 v60, v60, v61
	v_cvt_pk_bf16_f32 v61, v62, v63
	v_cvt_pk_bf16_f32 v62, v56, v57
	v_add_co_u32_e32 v56, vcc, s72, v144
	v_lshl_add_u64 v[64:65], v[144:145], 0, s[30:31]
	s_nop 0
	v_addc_co_u32_e32 v57, vcc, 0, v145, vcc
	v_cvt_pk_bf16_f32 v63, v58, v59
	global_store_dwordx4 v[56:57], v[60:63], off
	v_cvt_pk_bf16_f32 v48, v48, v49
	v_cvt_pk_bf16_f32 v49, v50, v51
	v_cvt_pk_bf16_f32 v50, v40, v41
	v_cvt_pk_bf16_f32 v51, v42, v43
	global_store_dwordx4 v[64:65], v[48:51], off offset:256
	v_cvt_pk_bf16_f32 v40, v52, v53
	v_cvt_pk_bf16_f32 v41, v54, v55
	v_cvt_pk_bf16_f32 v42, v44, v45
	v_add_co_u32_e32 v44, vcc, s73, v144
	s_nop 0
	v_lshl_add_u64 v[48:49], v[144:145], 0, s[36:37]
	v_addc_co_u32_e32 v45, vcc, 0, v145, vcc
	v_cvt_pk_bf16_f32 v43, v46, v47
	global_store_dwordx4 v[44:45], v[40:43], off
	v_cvt_pk_bf16_f32 v32, v32, v33
	v_cvt_pk_bf16_f32 v33, v34, v35
	v_cvt_pk_bf16_f32 v34, v24, v25
	v_cvt_pk_bf16_f32 v35, v26, v27
	global_store_dwordx4 v[48:49], v[32:35], off offset:256
	v_cvt_pk_bf16_f32 v24, v36, v37
	v_cvt_pk_bf16_f32 v25, v38, v39
	v_cvt_pk_bf16_f32 v26, v28, v29
	v_add_co_u32_e32 v28, vcc, s74, v144
	s_nop 0
	v_lshl_add_u64 v[32:33], v[144:145], 0, s[44:45]
	v_addc_co_u32_e32 v29, vcc, 0, v145, vcc
	v_cvt_pk_bf16_f32 v27, v30, v31
	global_store_dwordx4 v[28:29], v[24:27], off
	v_cvt_pk_bf16_f32 v16, v16, v17
	v_cvt_pk_bf16_f32 v17, v18, v19
	v_cvt_pk_bf16_f32 v18, v8, v9
	v_cvt_pk_bf16_f32 v19, v10, v11
	global_store_dwordx4 v[32:33], v[16:19], off offset:256
	v_cvt_pk_bf16_f32 v8, v20, v21
	v_cvt_pk_bf16_f32 v9, v22, v23
	v_cvt_pk_bf16_f32 v10, v12, v13
	v_add_co_u32_e32 v12, vcc, s75, v144
	s_nop 0
	v_lshl_add_u64 v[16:17], v[144:145], 0, s[46:47]
	v_addc_co_u32_e32 v13, vcc, 0, v145, vcc
	s_and_b64 vcc, exec, s[10:11]
	s_mov_b64 s[10:11], -1
	v_cvt_pk_bf16_f32 v11, v14, v15
	global_store_dwordx4 v[12:13], v[8:11], off
	v_cvt_pk_bf16_f32 v4, v4, v5
	v_cvt_pk_bf16_f32 v5, v6, v7
	v_cvt_pk_bf16_f32 v6, v0, v1
	v_cvt_pk_bf16_f32 v7, v2, v3
	global_store_dwordx4 v[16:17], v[4:7], off offset:256
	s_cbranch_vccnz .LBB0_792
	s_andn2_b64 vcc, exec, s[0:1]
	s_cbranch_vccnz .LBB0_791
	s_barrier
	s_branch .LBB0_791

.LBB0_1034:
	s_and_b64 vcc, exec, s[10:11]
	s_cbranch_vccnz .Lepi_wt_4
	v_lshl_add_u32 v152, s84, 8, v146
	v_lshl_or_b32 v144, s85, 8, v148
	v_ashrrev_i32_e32 v145, 31, v144
	v_ashrrev_i32_e32 v153, 31, v152
	v_lshl_add_u64 v[154:155], v[144:145], 1, s[24:25]
	v_lshlrev_b64 v[144:145], 11, v[152:153]
	v_lshl_add_u64 v[144:145], v[154:155], 0, v[144:145]
	s_nop 15
	s_nop 7
	v_cvt_pk_bf16_f32 v124, v124, v125
	v_cvt_pk_bf16_f32 v125, v126, v127
	v_cvt_pk_bf16_f32 v126, v120, v121
	v_cvt_pk_bf16_f32 v127, v122, v123
	global_store_dwordx4 v[144:145], v[124:127], off
	v_cvt_pk_bf16_f32 v112, v112, v113
	v_cvt_pk_bf16_f32 v113, v114, v115
	v_cvt_pk_bf16_f32 v114, v104, v105
	v_or_b32_e32 v104, 16, v152
	v_ashrrev_i32_e32 v105, 31, v104
	v_lshlrev_b64 v[104:105], 11, v[104:105]
	v_cvt_pk_bf16_f32 v115, v106, v107
	global_store_dwordx4 v[144:145], v[112:115], off offset:256
	s_nop 1
	v_lshl_add_u64 v[112:113], v[154:155], 0, v[104:105]
	v_cvt_pk_bf16_f32 v104, v116, v117
	v_cvt_pk_bf16_f32 v105, v118, v119
	v_cvt_pk_bf16_f32 v106, v108, v109
	v_cvt_pk_bf16_f32 v107, v110, v111
	global_store_dwordx4 v[112:113], v[104:107], off
	v_cvt_pk_bf16_f32 v96, v96, v97
	v_cvt_pk_bf16_f32 v97, v98, v99
	v_cvt_pk_bf16_f32 v98, v88, v89
	v_or_b32_e32 v88, 32, v152
	v_ashrrev_i32_e32 v89, 31, v88
	v_lshlrev_b64 v[88:89], 11, v[88:89]
	v_cvt_pk_bf16_f32 v99, v90, v91
	global_store_dwordx4 v[112:113], v[96:99], off offset:256
	s_nop 1
	v_lshl_add_u64 v[96:97], v[154:155], 0, v[88:89]
	v_cvt_pk_bf16_f32 v88, v100, v101
	v_cvt_pk_bf16_f32 v89, v102, v103
	v_cvt_pk_bf16_f32 v90, v92, v93
	v_cvt_pk_bf16_f32 v91, v94, v95
	global_store_dwordx4 v[96:97], v[88:91], off
	v_cvt_pk_bf16_f32 v80, v80, v81
	v_cvt_pk_bf16_f32 v81, v82, v83
	v_cvt_pk_bf16_f32 v82, v72, v73
	v_or_b32_e32 v72, 48, v152
	v_ashrrev_i32_e32 v73, 31, v72
	v_lshlrev_b64 v[72:73], 11, v[72:73]
	v_cvt_pk_bf16_f32 v83, v74, v75
	global_store_dwordx4 v[96:97], v[80:83], off offset:256
	s_nop 1
	v_lshl_add_u64 v[80:81], v[154:155], 0, v[72:73]
	v_cvt_pk_bf16_f32 v72, v84, v85
	v_cvt_pk_bf16_f32 v73, v86, v87
	v_cvt_pk_bf16_f32 v74, v76, v77
	v_cvt_pk_bf16_f32 v75, v78, v79
	global_store_dwordx4 v[80:81], v[72:75], off
	v_cvt_pk_bf16_f32 v68, v68, v69
	v_cvt_pk_bf16_f32 v69, v70, v71
	v_cvt_pk_bf16_f32 v70, v64, v65
	v_cvt_pk_bf16_f32 v71, v66, v67
	global_store_dwordx4 v[80:81], v[68:71], off offset:256
	v_cvt_pk_bf16_f32 v60, v60, v61
	v_cvt_pk_bf16_f32 v61, v62, v63
	v_cvt_pk_bf16_f32 v62, v56, v57
	v_add_co_u32_e32 v56, vcc, s74, v144
	v_lshl_add_u64 v[64:65], v[144:145], 0, s[36:37]
	s_nop 0
	v_addc_co_u32_e32 v57, vcc, 0, v145, vcc
	v_cvt_pk_bf16_f32 v63, v58, v59
	global_store_dwordx4 v[56:57], v[60:63], off
	v_cvt_pk_bf16_f32 v48, v48, v49
	v_cvt_pk_bf16_f32 v49, v50, v51
	v_cvt_pk_bf16_f32 v50, v40, v41
	v_cvt_pk_bf16_f32 v51, v42, v43
	global_store_dwordx4 v[64:65], v[48:51], off offset:256
	v_cvt_pk_bf16_f32 v40, v52, v53
	v_cvt_pk_bf16_f32 v41, v54, v55
	v_cvt_pk_bf16_f32 v42, v44, v45
	v_add_co_u32_e32 v44, vcc, s75, v144
	s_nop 0
	v_lshl_add_u64 v[48:49], v[144:145], 0, s[44:45]
	v_addc_co_u32_e32 v45, vcc, 0, v145, vcc
	v_cvt_pk_bf16_f32 v43, v46, v47
	global_store_dwordx4 v[44:45], v[40:43], off
	v_cvt_pk_bf16_f32 v32, v32, v33
	v_cvt_pk_bf16_f32 v33, v34, v35
	v_cvt_pk_bf16_f32 v34, v24, v25
	v_cvt_pk_bf16_f32 v35, v26, v27
	global_store_dwordx4 v[48:49], v[32:35], off offset:256
	v_cvt_pk_bf16_f32 v24, v36, v37
	v_cvt_pk_bf16_f32 v25, v38, v39
	v_cvt_pk_bf16_f32 v26, v28, v29
	v_add_co_u32_e32 v28, vcc, s76, v144
	s_nop 0
	v_lshl_add_u64 v[32:33], v[144:145], 0, s[46:47]
	v_addc_co_u32_e32 v29, vcc, 0, v145, vcc
	v_cvt_pk_bf16_f32 v27, v30, v31
	global_store_dwordx4 v[28:29], v[24:27], off
	v_cvt_pk_bf16_f32 v16, v16, v17
	v_cvt_pk_bf16_f32 v17, v18, v19
	v_cvt_pk_bf16_f32 v18, v8, v9
	v_cvt_pk_bf16_f32 v19, v10, v11
	global_store_dwordx4 v[32:33], v[16:19], off offset:256
	v_cvt_pk_bf16_f32 v8, v20, v21
	v_cvt_pk_bf16_f32 v9, v22, v23
	v_cvt_pk_bf16_f32 v10, v12, v13
	v_add_co_u32_e32 v12, vcc, s77, v144
	s_nop 0
	v_lshl_add_u64 v[16:17], v[144:145], 0, s[48:49]
	v_addc_co_u32_e32 v13, vcc, 0, v145, vcc
	s_and_b64 vcc, exec, s[10:11]
	s_mov_b64 s[10:11], -1
	v_cvt_pk_bf16_f32 v11, v14, v15
	global_store_dwordx4 v[12:13], v[8:11], off
	v_cvt_pk_bf16_f32 v4, v4, v5
	v_cvt_pk_bf16_f32 v5, v6, v7
	v_cvt_pk_bf16_f32 v6, v0, v1
	v_cvt_pk_bf16_f32 v7, v2, v3
	global_store_dwordx4 v[16:17], v[4:7], off offset:256
	s_cbranch_vccnz .LBB0_1019
	s_andn2_b64 vcc, exec, s[0:1]
	s_cbranch_vccnz .LBB0_1018
	s_barrier
	s_branch .LBB0_1018

.LBB0_1165:
	s_andn2_b64 vcc, exec, s[10:11]
	s_cbranch_vccnz .Lepi_wt_5
	s_lshl_b32 s49, s59, 8
	s_or_b32 s49, s49, s74
	v_lshl_add_u32 v152, s58, 8, v146
	s_ashr_i32 s58, s49, 6
	s_ashr_i32 s59, s58, 31
	s_lshl_b64 s[60:61], s[58:59], 22
	s_cmp_lt_i32 s58, 16
	s_cselect_b64 vcc, -1, 0
	v_cndmask_b32_e32 v156, 1.0, v151, vcc
	v_pk_mul_f32 v[124:125], v[156:157], v[124:125] op_sel_hi:[0,1]
	v_ashrrev_i32_e32 v153, 31, v152
	v_lshl_add_u64 v[154:155], v[136:137], 0, s[60:61]
	v_pk_mul_f32 v[126:127], v[156:157], v[126:127] op_sel_hi:[0,1]
	v_pk_mul_f32 v[158:159], v[156:157], v[122:123] op_sel_hi:[0,1]
	v_pk_mul_f32 v[122:123], v[156:157], v[120:121] op_sel_hi:[0,1]
	v_cvt_pk_bf16_f32 v120, v124, v125
	v_lshlrev_b64 v[124:125], 7, v[152:153]
	v_cvt_pk_bf16_f32 v121, v126, v127
	v_lshl_add_u64 v[126:127], v[154:155], 0, v[124:125]
	v_pk_mul_f32 v[116:117], v[156:157], v[116:117] op_sel_hi:[0,1]
	v_cvt_pk_bf16_f32 v122, v122, v123
	v_cvt_pk_bf16_f32 v123, v158, v159
	global_store_dwordx4 v[126:127], v[120:123], off
	v_pk_mul_f32 v[118:119], v[156:157], v[118:119] op_sel_hi:[0,1]
	v_pk_mul_f32 v[108:109], v[156:157], v[108:109] op_sel_hi:[0,1]
	v_pk_mul_f32 v[120:121], v[156:157], v[114:115] op_sel_hi:[0,1]
	v_pk_mul_f32 v[114:115], v[156:157], v[112:113] op_sel_hi:[0,1]
	v_cvt_pk_bf16_f32 v112, v116, v117
	v_or_b32_e32 v116, 16, v152
	v_ashrrev_i32_e32 v117, 31, v116
	v_lshlrev_b64 v[116:117], 7, v[116:117]
	v_cvt_pk_bf16_f32 v113, v118, v119
	v_lshl_add_u64 v[118:119], v[154:155], 0, v[116:117]
	v_cvt_pk_bf16_f32 v114, v114, v115
	v_cvt_pk_bf16_f32 v115, v120, v121
	global_store_dwordx4 v[118:119], v[112:115], off
	v_pk_mul_f32 v[110:111], v[156:157], v[110:111] op_sel_hi:[0,1]
	v_pk_mul_f32 v[100:101], v[156:157], v[100:101] op_sel_hi:[0,1]
	v_pk_mul_f32 v[112:113], v[156:157], v[106:107] op_sel_hi:[0,1]
	v_pk_mul_f32 v[106:107], v[156:157], v[104:105] op_sel_hi:[0,1]
	v_cvt_pk_bf16_f32 v104, v108, v109
	v_or_b32_e32 v108, 32, v152
	v_ashrrev_i32_e32 v109, 31, v108
	v_lshlrev_b64 v[108:109], 7, v[108:109]
	v_cvt_pk_bf16_f32 v105, v110, v111
	v_lshl_add_u64 v[110:111], v[154:155], 0, v[108:109]
	v_cvt_pk_bf16_f32 v106, v106, v107
	v_cvt_pk_bf16_f32 v107, v112, v113
	global_store_dwordx4 v[110:111], v[104:107], off
	v_pk_mul_f32 v[102:103], v[156:157], v[102:103] op_sel_hi:[0,1]
	v_pk_mul_f32 v[92:93], v[156:157], v[92:93] op_sel_hi:[0,1]
	v_pk_mul_f32 v[104:105], v[156:157], v[98:99] op_sel_hi:[0,1]
	v_pk_mul_f32 v[98:99], v[156:157], v[96:97] op_sel_hi:[0,1]
	v_cvt_pk_bf16_f32 v96, v100, v101
	v_or_b32_e32 v100, 48, v152
	v_ashrrev_i32_e32 v101, 31, v100
	v_lshlrev_b64 v[100:101], 7, v[100:101]
	v_cvt_pk_bf16_f32 v97, v102, v103
	v_lshl_add_u64 v[102:103], v[154:155], 0, v[100:101]
	v_cvt_pk_bf16_f32 v98, v98, v99
	v_cvt_pk_bf16_f32 v99, v104, v105
	global_store_dwordx4 v[102:103], v[96:99], off
	v_pk_mul_f32 v[94:95], v[156:157], v[94:95] op_sel_hi:[0,1]
	v_pk_mul_f32 v[84:85], v[156:157], v[84:85] op_sel_hi:[0,1]
	v_pk_mul_f32 v[96:97], v[156:157], v[90:91] op_sel_hi:[0,1]
	v_pk_mul_f32 v[90:91], v[156:157], v[88:89] op_sel_hi:[0,1]
	v_cvt_pk_bf16_f32 v88, v92, v93
	v_lshl_add_u64 v[92:93], v[124:125], 0, s[18:19]
	v_cvt_pk_bf16_f32 v89, v94, v95
	v_lshl_add_u64 v[94:95], v[154:155], 0, v[92:93]
	v_cvt_pk_bf16_f32 v90, v90, v91
	v_cvt_pk_bf16_f32 v91, v96, v97
	global_store_dwordx4 v[94:95], v[88:91], off
	v_pk_mul_f32 v[86:87], v[156:157], v[86:87] op_sel_hi:[0,1]
	s_or_b32 s58, s58, 2
	v_pk_mul_f32 v[88:89], v[156:157], v[82:83] op_sel_hi:[0,1]
	v_pk_mul_f32 v[82:83], v[156:157], v[80:81] op_sel_hi:[0,1]
	v_cvt_pk_bf16_f32 v80, v84, v85
	v_lshl_add_u64 v[84:85], v[124:125], 0, s[36:37]
	v_cvt_pk_bf16_f32 v81, v86, v87
	v_lshl_add_u64 v[86:87], v[154:155], 0, v[84:85]
	v_pk_mul_f32 v[76:77], v[156:157], v[76:77] op_sel_hi:[0,1]
	s_ashr_i32 s59, s58, 31
	v_cvt_pk_bf16_f32 v82, v82, v83
	v_cvt_pk_bf16_f32 v83, v88, v89
	global_store_dwordx4 v[86:87], v[80:83], off
	v_pk_mul_f32 v[78:79], v[156:157], v[78:79] op_sel_hi:[0,1]
	s_lshl_b64 s[60:61], s[58:59], 22
	v_pk_mul_f32 v[80:81], v[156:157], v[74:75] op_sel_hi:[0,1]
	v_pk_mul_f32 v[74:75], v[156:157], v[72:73] op_sel_hi:[0,1]
	v_cvt_pk_bf16_f32 v72, v76, v77
	v_lshl_add_u64 v[76:77], v[124:125], 0, s[44:45]
	v_cvt_pk_bf16_f32 v73, v78, v79
	v_lshl_add_u64 v[78:79], v[154:155], 0, v[76:77]
	v_pk_mul_f32 v[60:61], v[156:157], v[60:61] op_sel_hi:[0,1]
	s_cmp_lt_i32 s58, 16
	v_cvt_pk_bf16_f32 v74, v74, v75
	v_cvt_pk_bf16_f32 v75, v80, v81
	global_store_dwordx4 v[78:79], v[72:75], off
	v_pk_mul_f32 v[62:63], v[156:157], v[62:63] op_sel_hi:[0,1]
	s_cselect_b64 vcc, -1, 0
	v_pk_mul_f32 v[72:73], v[156:157], v[58:59] op_sel_hi:[0,1]
	v_pk_mul_f32 v[58:59], v[156:157], v[56:57] op_sel_hi:[0,1]
	v_cvt_pk_bf16_f32 v56, v60, v61
	v_lshl_add_u64 v[60:61], v[124:125], 0, s[46:47]
	v_cvt_pk_bf16_f32 v57, v62, v63
	v_cvt_pk_bf16_f32 v58, v58, v59
	v_cvt_pk_bf16_f32 v59, v72, v73
	v_lshl_add_u64 v[62:63], v[154:155], 0, v[60:61]
	v_cndmask_b32_e32 v72, 1.0, v151, vcc
	global_store_dwordx4 v[62:63], v[56:59], off
	v_lshl_add_u64 v[62:63], v[136:137], 0, s[60:61]
	v_pk_mul_f32 v[64:65], v[72:73], v[64:65] op_sel_hi:[0,1]
	v_pk_mul_f32 v[58:59], v[72:73], v[70:71] op_sel_hi:[0,1]
	v_pk_mul_f32 v[56:57], v[72:73], v[68:69] op_sel_hi:[0,1]
	v_cvt_pk_bf16_f32 v56, v56, v57
	v_cvt_pk_bf16_f32 v57, v58, v59
	v_cvt_pk_bf16_f32 v58, v64, v65
	v_lshl_add_u64 v[64:65], v[62:63], 0, v[124:125]
	v_pk_mul_f32 v[52:53], v[72:73], v[52:53] op_sel_hi:[0,1]
	v_pk_mul_f32 v[66:67], v[72:73], v[66:67] op_sel_hi:[0,1]
	v_cvt_pk_bf16_f32 v59, v66, v67
	global_store_dwordx4 v[64:65], v[56:59], off
	v_pk_mul_f32 v[54:55], v[72:73], v[54:55] op_sel_hi:[0,1]
	v_pk_mul_f32 v[44:45], v[72:73], v[44:45] op_sel_hi:[0,1]
	v_pk_mul_f32 v[56:57], v[72:73], v[50:51] op_sel_hi:[0,1]
	v_pk_mul_f32 v[50:51], v[72:73], v[48:49] op_sel_hi:[0,1]
	v_cvt_pk_bf16_f32 v48, v52, v53
	v_cvt_pk_bf16_f32 v49, v54, v55
	v_lshl_add_u64 v[52:53], v[62:63], 0, v[116:117]
	v_cvt_pk_bf16_f32 v50, v50, v51
	v_cvt_pk_bf16_f32 v51, v56, v57
	global_store_dwordx4 v[52:53], v[48:51], off
	v_pk_mul_f32 v[46:47], v[72:73], v[46:47] op_sel_hi:[0,1]
	v_pk_mul_f32 v[36:37], v[72:73], v[36:37] op_sel_hi:[0,1]
	v_pk_mul_f32 v[48:49], v[72:73], v[42:43] op_sel_hi:[0,1]
	v_pk_mul_f32 v[42:43], v[72:73], v[40:41] op_sel_hi:[0,1]
	v_cvt_pk_bf16_f32 v40, v44, v45
	v_cvt_pk_bf16_f32 v41, v46, v47
	v_lshl_add_u64 v[44:45], v[62:63], 0, v[108:109]
	v_cvt_pk_bf16_f32 v42, v42, v43
	v_cvt_pk_bf16_f32 v43, v48, v49
	global_store_dwordx4 v[44:45], v[40:43], off
	v_pk_mul_f32 v[38:39], v[72:73], v[38:39] op_sel_hi:[0,1]
	v_pk_mul_f32 v[28:29], v[72:73], v[28:29] op_sel_hi:[0,1]
	v_pk_mul_f32 v[40:41], v[72:73], v[34:35] op_sel_hi:[0,1]
	v_pk_mul_f32 v[34:35], v[72:73], v[32:33] op_sel_hi:[0,1]
	v_cvt_pk_bf16_f32 v32, v36, v37
	v_cvt_pk_bf16_f32 v33, v38, v39
	v_lshl_add_u64 v[36:37], v[62:63], 0, v[100:101]
	v_cvt_pk_bf16_f32 v34, v34, v35
	v_cvt_pk_bf16_f32 v35, v40, v41
	global_store_dwordx4 v[36:37], v[32:35], off
	v_pk_mul_f32 v[30:31], v[72:73], v[30:31] op_sel_hi:[0,1]
	v_pk_mul_f32 v[20:21], v[72:73], v[20:21] op_sel_hi:[0,1]
	v_pk_mul_f32 v[32:33], v[72:73], v[26:27] op_sel_hi:[0,1]
	v_pk_mul_f32 v[26:27], v[72:73], v[24:25] op_sel_hi:[0,1]
	v_cvt_pk_bf16_f32 v24, v28, v29
	v_cvt_pk_bf16_f32 v25, v30, v31
	v_lshl_add_u64 v[28:29], v[62:63], 0, v[92:93]
	v_cvt_pk_bf16_f32 v26, v26, v27
	v_cvt_pk_bf16_f32 v27, v32, v33
	global_store_dwordx4 v[28:29], v[24:27], off
	v_pk_mul_f32 v[22:23], v[72:73], v[22:23] op_sel_hi:[0,1]
	v_pk_mul_f32 v[12:13], v[72:73], v[12:13] op_sel_hi:[0,1]
	v_pk_mul_f32 v[24:25], v[72:73], v[18:19] op_sel_hi:[0,1]
	v_pk_mul_f32 v[18:19], v[72:73], v[16:17] op_sel_hi:[0,1]
	v_cvt_pk_bf16_f32 v16, v20, v21
	v_cvt_pk_bf16_f32 v17, v22, v23
	v_lshl_add_u64 v[20:21], v[62:63], 0, v[84:85]
	v_cvt_pk_bf16_f32 v18, v18, v19
	v_cvt_pk_bf16_f32 v19, v24, v25
	global_store_dwordx4 v[20:21], v[16:19], off
	v_pk_mul_f32 v[14:15], v[72:73], v[14:15] op_sel_hi:[0,1]
	v_pk_mul_f32 v[4:5], v[72:73], v[4:5] op_sel_hi:[0,1]
	v_pk_mul_f32 v[16:17], v[72:73], v[10:11] op_sel_hi:[0,1]
	v_pk_mul_f32 v[10:11], v[72:73], v[8:9] op_sel_hi:[0,1]
	v_cvt_pk_bf16_f32 v8, v12, v13
	v_cvt_pk_bf16_f32 v9, v14, v15
	v_lshl_add_u64 v[12:13], v[62:63], 0, v[76:77]
	v_cvt_pk_bf16_f32 v10, v10, v11
	v_cvt_pk_bf16_f32 v11, v16, v17
	global_store_dwordx4 v[12:13], v[8:11], off
	s_andn2_b64 vcc, exec, s[10:11]
	s_mov_b64 s[10:11], -1
	v_pk_mul_f32 v[8:9], v[72:73], v[2:3] op_sel_hi:[0,1]
	v_pk_mul_f32 v[2:3], v[72:73], v[0:1] op_sel_hi:[0,1]
	v_cvt_pk_bf16_f32 v0, v4, v5
	v_lshl_add_u64 v[4:5], v[62:63], 0, v[60:61]
	v_pk_mul_f32 v[6:7], v[72:73], v[6:7] op_sel_hi:[0,1]
	v_cvt_pk_bf16_f32 v1, v6, v7
	v_cvt_pk_bf16_f32 v2, v2, v3
	v_cvt_pk_bf16_f32 v3, v8, v9
	global_store_dwordx4 v[4:5], v[0:3], off
	s_cbranch_vccnz .LBB0_1154
	s_andn2_b64 vcc, exec, s[0:1]
	s_cbranch_vccnz .LBB0_1153
	s_barrier
	s_branch .LBB0_1153

.LBB0_1314:
	s_andn2_b64 vcc, exec, s[10:11]
	s_cbranch_vccnz .Lepi_wt_6
	v_lshl_add_u32 v152, s54, 8, v146
	v_lshl_or_b32 v144, s77, 8, v148
	v_ashrrev_i32_e32 v145, 31, v144
	v_ashrrev_i32_e32 v153, 31, v152
	v_lshl_add_u64 v[154:155], v[144:145], 1, s[24:25]
	v_lshlrev_b64 v[144:145], 11, v[152:153]
	v_lshl_add_u64 v[144:145], v[154:155], 0, v[144:145]
	s_nop 15
	s_nop 7
	v_cvt_pk_bf16_f32 v124, v124, v125
	v_cvt_pk_bf16_f32 v125, v126, v127
	v_cvt_pk_bf16_f32 v126, v120, v121
	v_cvt_pk_bf16_f32 v127, v122, v123
	global_store_dwordx4 v[144:145], v[124:127], off
	v_cvt_pk_bf16_f32 v112, v112, v113
	v_cvt_pk_bf16_f32 v113, v114, v115
	v_cvt_pk_bf16_f32 v114, v104, v105
	v_or_b32_e32 v104, 16, v152
	v_ashrrev_i32_e32 v105, 31, v104
	v_lshlrev_b64 v[104:105], 11, v[104:105]
	v_cvt_pk_bf16_f32 v115, v106, v107
	global_store_dwordx4 v[144:145], v[112:115], off offset:256
	s_nop 1
	v_lshl_add_u64 v[112:113], v[154:155], 0, v[104:105]
	v_cvt_pk_bf16_f32 v104, v116, v117
	v_cvt_pk_bf16_f32 v105, v118, v119
	v_cvt_pk_bf16_f32 v106, v108, v109
	v_cvt_pk_bf16_f32 v107, v110, v111
	global_store_dwordx4 v[112:113], v[104:107], off
	v_cvt_pk_bf16_f32 v96, v96, v97
	v_cvt_pk_bf16_f32 v97, v98, v99
	v_cvt_pk_bf16_f32 v98, v88, v89
	v_or_b32_e32 v88, 32, v152
	v_ashrrev_i32_e32 v89, 31, v88
	v_lshlrev_b64 v[88:89], 11, v[88:89]
	v_cvt_pk_bf16_f32 v99, v90, v91
	global_store_dwordx4 v[112:113], v[96:99], off offset:256
	s_nop 1
	v_lshl_add_u64 v[96:97], v[154:155], 0, v[88:89]
	v_cvt_pk_bf16_f32 v88, v100, v101
	v_cvt_pk_bf16_f32 v89, v102, v103
	v_cvt_pk_bf16_f32 v90, v92, v93
	v_cvt_pk_bf16_f32 v91, v94, v95
	global_store_dwordx4 v[96:97], v[88:91], off
	v_cvt_pk_bf16_f32 v80, v80, v81
	v_cvt_pk_bf16_f32 v81, v82, v83
	v_cvt_pk_bf16_f32 v82, v72, v73
	v_or_b32_e32 v72, 48, v152
	v_ashrrev_i32_e32 v73, 31, v72
	v_lshlrev_b64 v[72:73], 11, v[72:73]
	v_cvt_pk_bf16_f32 v83, v74, v75
	global_store_dwordx4 v[96:97], v[80:83], off offset:256
	s_nop 1
	v_lshl_add_u64 v[80:81], v[154:155], 0, v[72:73]
	v_cvt_pk_bf16_f32 v72, v84, v85
	v_cvt_pk_bf16_f32 v73, v86, v87
	v_cvt_pk_bf16_f32 v74, v76, v77
	v_cvt_pk_bf16_f32 v75, v78, v79
	global_store_dwordx4 v[80:81], v[72:75], off
	v_cvt_pk_bf16_f32 v68, v68, v69
	v_cvt_pk_bf16_f32 v69, v70, v71
	v_cvt_pk_bf16_f32 v70, v64, v65
	v_cvt_pk_bf16_f32 v71, v66, v67
	global_store_dwordx4 v[80:81], v[68:71], off offset:256
	v_cvt_pk_bf16_f32 v60, v60, v61
	v_cvt_pk_bf16_f32 v61, v62, v63
	v_cvt_pk_bf16_f32 v62, v56, v57
	v_add_co_u32_e32 v56, vcc, s73, v144
	v_lshl_add_u64 v[64:65], v[144:145], 0, s[0:1]
	s_nop 0
	v_addc_co_u32_e32 v57, vcc, 0, v145, vcc
	v_cvt_pk_bf16_f32 v63, v58, v59
	global_store_dwordx4 v[56:57], v[60:63], off
	v_cvt_pk_bf16_f32 v48, v48, v49
	v_cvt_pk_bf16_f32 v49, v50, v51
	v_cvt_pk_bf16_f32 v50, v40, v41
	v_cvt_pk_bf16_f32 v51, v42, v43
	global_store_dwordx4 v[64:65], v[48:51], off offset:256
	v_cvt_pk_bf16_f32 v40, v52, v53
	v_cvt_pk_bf16_f32 v41, v54, v55
	v_cvt_pk_bf16_f32 v42, v44, v45
	v_add_co_u32_e32 v44, vcc, s74, v144
	s_nop 0
	v_lshl_add_u64 v[48:49], v[144:145], 0, s[30:31]
	v_addc_co_u32_e32 v45, vcc, 0, v145, vcc
	v_cvt_pk_bf16_f32 v43, v46, v47
	global_store_dwordx4 v[44:45], v[40:43], off
	v_cvt_pk_bf16_f32 v32, v32, v33
	v_cvt_pk_bf16_f32 v33, v34, v35
	v_cvt_pk_bf16_f32 v34, v24, v25
	v_cvt_pk_bf16_f32 v35, v26, v27
	global_store_dwordx4 v[48:49], v[32:35], off offset:256
	v_cvt_pk_bf16_f32 v24, v36, v37
	v_cvt_pk_bf16_f32 v25, v38, v39
	v_cvt_pk_bf16_f32 v26, v28, v29
	v_add_co_u32_e32 v28, vcc, s75, v144
	s_nop 0
	v_lshl_add_u64 v[32:33], v[144:145], 0, s[36:37]
	v_addc_co_u32_e32 v29, vcc, 0, v145, vcc
	v_cvt_pk_bf16_f32 v27, v30, v31
	global_store_dwordx4 v[28:29], v[24:27], off
	v_cvt_pk_bf16_f32 v16, v16, v17
	v_cvt_pk_bf16_f32 v17, v18, v19
	v_cvt_pk_bf16_f32 v18, v8, v9
	v_cvt_pk_bf16_f32 v19, v10, v11
	global_store_dwordx4 v[32:33], v[16:19], off offset:256
	v_cvt_pk_bf16_f32 v8, v20, v21
	v_cvt_pk_bf16_f32 v9, v22, v23
	v_cvt_pk_bf16_f32 v10, v12, v13
	v_add_co_u32_e32 v12, vcc, s76, v144
	s_nop 0
	v_lshl_add_u64 v[16:17], v[144:145], 0, s[44:45]
	v_addc_co_u32_e32 v13, vcc, 0, v145, vcc
	s_andn2_b64 vcc, exec, s[10:11]
	s_mov_b64 s[10:11], -1
	v_cvt_pk_bf16_f32 v11, v14, v15
	global_store_dwordx4 v[12:13], v[8:11], off
	v_cvt_pk_bf16_f32 v4, v4, v5
	v_cvt_pk_bf16_f32 v5, v6, v7
	v_cvt_pk_bf16_f32 v6, v0, v1
	v_cvt_pk_bf16_f32 v7, v2, v3
	global_store_dwordx4 v[16:17], v[4:7], off offset:256
	s_cbranch_vccnz .LBB0_1303
	s_andn2_b64 vcc, exec, s[12:13]
	s_cbranch_vccnz .LBB0_1302
	s_barrier
	s_branch .LBB0_1302

.LBB0_1517:
	s_and_b64 vcc, exec, s[6:7]
	s_cbranch_vccnz .Lepi_wt_7
	v_lshl_add_u32 v152, s72, 8, v146
	v_lshl_or_b32 v144, s73, 8, v148
	v_ashrrev_i32_e32 v145, 31, v144
	v_ashrrev_i32_e32 v153, 31, v152
	v_lshl_add_u64 v[154:155], v[144:145], 1, s[24:25]
	v_lshlrev_b64 v[144:145], 11, v[152:153]
	v_lshl_add_u64 v[144:145], v[154:155], 0, v[144:145]
	s_nop 15
	s_nop 7
	v_cvt_pk_bf16_f32 v124, v124, v125
	v_cvt_pk_bf16_f32 v125, v126, v127
	v_cvt_pk_bf16_f32 v126, v120, v121
	v_cvt_pk_bf16_f32 v127, v122, v123
	global_store_dwordx4 v[144:145], v[124:127], off
	v_cvt_pk_bf16_f32 v112, v112, v113
	v_cvt_pk_bf16_f32 v113, v114, v115
	v_cvt_pk_bf16_f32 v114, v104, v105
	v_or_b32_e32 v104, 16, v152
	v_ashrrev_i32_e32 v105, 31, v104
	v_lshlrev_b64 v[104:105], 11, v[104:105]
	v_cvt_pk_bf16_f32 v115, v106, v107
	global_store_dwordx4 v[144:145], v[112:115], off offset:256
	s_nop 1
	v_lshl_add_u64 v[112:113], v[154:155], 0, v[104:105]
	v_cvt_pk_bf16_f32 v104, v116, v117
	v_cvt_pk_bf16_f32 v105, v118, v119
	v_cvt_pk_bf16_f32 v106, v108, v109
	v_cvt_pk_bf16_f32 v107, v110, v111
	global_store_dwordx4 v[112:113], v[104:107], off
	v_cvt_pk_bf16_f32 v96, v96, v97
	v_cvt_pk_bf16_f32 v97, v98, v99
	v_cvt_pk_bf16_f32 v98, v88, v89
	v_or_b32_e32 v88, 32, v152
	v_ashrrev_i32_e32 v89, 31, v88
	v_lshlrev_b64 v[88:89], 11, v[88:89]
	v_cvt_pk_bf16_f32 v99, v90, v91
	global_store_dwordx4 v[112:113], v[96:99], off offset:256
	s_nop 1
	v_lshl_add_u64 v[96:97], v[154:155], 0, v[88:89]
	v_cvt_pk_bf16_f32 v88, v100, v101
	v_cvt_pk_bf16_f32 v89, v102, v103
	v_cvt_pk_bf16_f32 v90, v92, v93
	v_cvt_pk_bf16_f32 v91, v94, v95
	global_store_dwordx4 v[96:97], v[88:91], off
	v_cvt_pk_bf16_f32 v80, v80, v81
	v_cvt_pk_bf16_f32 v81, v82, v83
	v_cvt_pk_bf16_f32 v82, v72, v73
	v_or_b32_e32 v72, 48, v152
	v_ashrrev_i32_e32 v73, 31, v72
	v_lshlrev_b64 v[72:73], 11, v[72:73]
	v_cvt_pk_bf16_f32 v83, v74, v75
	global_store_dwordx4 v[96:97], v[80:83], off offset:256
	s_nop 1
	v_lshl_add_u64 v[80:81], v[154:155], 0, v[72:73]
	v_cvt_pk_bf16_f32 v72, v84, v85
	v_cvt_pk_bf16_f32 v73, v86, v87
	v_cvt_pk_bf16_f32 v74, v76, v77
	v_cvt_pk_bf16_f32 v75, v78, v79
	global_store_dwordx4 v[80:81], v[72:75], off
	v_cvt_pk_bf16_f32 v68, v68, v69
	v_cvt_pk_bf16_f32 v69, v70, v71
	v_cvt_pk_bf16_f32 v70, v64, v65
	v_cvt_pk_bf16_f32 v71, v66, v67
	global_store_dwordx4 v[80:81], v[68:71], off offset:256
	v_cvt_pk_bf16_f32 v60, v60, v61
	v_cvt_pk_bf16_f32 v61, v62, v63
	v_cvt_pk_bf16_f32 v62, v56, v57
	v_add_co_u32_e32 v56, vcc, s66, v144
	v_lshl_add_u64 v[64:65], v[144:145], 0, s[16:17]
	s_nop 0
	v_addc_co_u32_e32 v57, vcc, 0, v145, vcc
	v_cvt_pk_bf16_f32 v63, v58, v59
	global_store_dwordx4 v[56:57], v[60:63], off
	v_cvt_pk_bf16_f32 v48, v48, v49
	v_cvt_pk_bf16_f32 v49, v50, v51
	v_cvt_pk_bf16_f32 v50, v40, v41
	v_cvt_pk_bf16_f32 v51, v42, v43
	global_store_dwordx4 v[64:65], v[48:51], off offset:256
	v_cvt_pk_bf16_f32 v40, v52, v53
	v_cvt_pk_bf16_f32 v41, v54, v55
	v_cvt_pk_bf16_f32 v42, v44, v45
	v_add_co_u32_e32 v44, vcc, s67, v144
	s_nop 0
	v_lshl_add_u64 v[48:49], v[144:145], 0, s[18:19]
	v_addc_co_u32_e32 v45, vcc, 0, v145, vcc
	v_cvt_pk_bf16_f32 v43, v46, v47
	global_store_dwordx4 v[44:45], v[40:43], off
	v_cvt_pk_bf16_f32 v32, v32, v33
	v_cvt_pk_bf16_f32 v33, v34, v35
	v_cvt_pk_bf16_f32 v34, v24, v25
	v_cvt_pk_bf16_f32 v35, v26, v27
	global_store_dwordx4 v[48:49], v[32:35], off offset:256
	v_cvt_pk_bf16_f32 v24, v36, v37
	v_cvt_pk_bf16_f32 v25, v38, v39
	v_cvt_pk_bf16_f32 v26, v28, v29
	v_add_co_u32_e32 v28, vcc, s68, v144
	s_nop 0
	v_lshl_add_u64 v[32:33], v[144:145], 0, s[30:31]
	v_addc_co_u32_e32 v29, vcc, 0, v145, vcc
	v_cvt_pk_bf16_f32 v27, v30, v31
	global_store_dwordx4 v[28:29], v[24:27], off
	v_cvt_pk_bf16_f32 v16, v16, v17
	v_cvt_pk_bf16_f32 v17, v18, v19
	v_cvt_pk_bf16_f32 v18, v8, v9
	v_cvt_pk_bf16_f32 v19, v10, v11
	global_store_dwordx4 v[32:33], v[16:19], off offset:256
	v_cvt_pk_bf16_f32 v8, v20, v21
	v_cvt_pk_bf16_f32 v9, v22, v23
	v_cvt_pk_bf16_f32 v10, v12, v13
	v_add_co_u32_e32 v12, vcc, s69, v144
	s_nop 0
	v_lshl_add_u64 v[16:17], v[144:145], 0, s[36:37]
	v_addc_co_u32_e32 v13, vcc, 0, v145, vcc
	s_and_b64 vcc, exec, s[6:7]
	s_mov_b64 s[6:7], -1
	v_cvt_pk_bf16_f32 v11, v14, v15
	global_store_dwordx4 v[12:13], v[8:11], off
	v_cvt_pk_bf16_f32 v4, v4, v5
	v_cvt_pk_bf16_f32 v5, v6, v7
	v_cvt_pk_bf16_f32 v6, v0, v1
	v_cvt_pk_bf16_f32 v7, v2, v3
	global_store_dwordx4 v[16:17], v[4:7], off offset:256
	s_cbranch_vccnz .LBB0_1502
	s_andn2_b64 vcc, exec, s[0:1]
	s_cbranch_vccnz .LBB0_1501
	s_barrier
	s_branch .LBB0_1501
